# GEMM phase prologues: K-tile 1's six LDS-DMA pieces issued before the first wait (vmcnt 2 -> 8 after them), one memory latency less per phase
# speedup vs baseline: 1.0010x; 1.0010x over previous
.LBB5_238:
	s_add_u32 s14, s72, 0xc000000
	s_addc_u32 s15, s73, 0
	s_add_u32 s55, s72, 0x10000000
	s_addc_u32 s56, s73, 0
	s_add_u32 s16, s72, 0x2700000
	s_addc_u32 s17, s73, 0
	s_lshl_b32 s57, s0, 6
	s_lshl_b32 s3, s0, 13
	v_readlane_b32 s0, v250, 29
	s_lshl_b32 s0, s0, 5
	s_and_b32 s5, s0, 0x60
	s_lshr_b32 s7, s5, 3
	v_readlane_b32 s0, v250, 0
	s_cmpk_lt_u32 s0, 0x100
	s_mov_b64 s[20:21], 0x80
	s_cselect_b64 s[18:19], -1, 0
	v_lshl_add_u64 v[6:7], v[6:7], 0, s[20:21]
	s_add_i32 m0, s51, 0x18000
	s_ashr_i32 s58, s90, 31
	s_ashr_i32 s59, s2, 31
	global_load_lds_dwordx4 v[6:7], off
	v_lshl_add_u64 v[4:5], v[4:5], 0, s[20:21]
	s_add_i32 m0, s51, 0x1a000
	s_add_i32 s62, s51, 0x8000
	s_add_i32 s63, s51, 0xa000
	global_load_lds_dwordx4 v[4:5], off
	v_lshl_add_u64 v[2:3], v[2:3], 0, s[20:21]
	s_mov_b32 m0, s62
	s_add_u32 s0, s44, 0x40080
	global_load_lds_dwordx4 v[2:3], off
	v_lshl_add_u64 v[0:1], v[0:1], 0, s[20:21]
	s_mov_b32 m0, s63
	s_addc_u32 s1, s45, 0
	global_load_lds_dwordx4 v[0:1], off
	v_lshl_add_u64 v[0:1], s[0:1], 0, v[130:131]
	s_add_i32 m0, s51, 0x1c000
	v_and_b32_e32 v139, 15, v9
	global_load_lds_dwordx4 v[0:1], off
	v_lshl_add_u64 v[0:1], s[0:1], 0, v[134:135]
	s_add_i32 m0, s51, 0x1e000
	v_lshrrev_b32_e32 v2, 6, v9
	global_load_lds_dwordx4 v[0:1], off
	s_waitcnt vmcnt(8)
	s_barrier
	v_lshrrev_b32_e32 v0, 1, v9
	v_and_b32_e32 v1, 56, v0
	v_and_b32_e32 v138, 8, v0
	v_lshlrev_b32_e32 v0, 14, v8
	v_and_b32_e32 v0, 0xffff8000, v0
	v_add_u32_e32 v174, s5, v1
	v_lshl_add_u32 v0, v10, 11, v0
	v_and_b32_e32 v1, 1, v8
	v_lshl_or_b32 v0, v1, 6, v0
	v_lshlrev_b32_e32 v6, 2, v9
	v_lshl_add_u32 v140, v11, 1, v0
	v_lshlrev_b32_e32 v0, 14, v12
	v_and_b32_e32 v3, 48, v9
	v_lshlrev_b32_e32 v4, 10, v2
	v_lshlrev_b32_e32 v5, 6, v139
	v_and_b32_e32 v6, 32, v6
	v_or_b32_e32 v2, s7, v2
	v_and_b32_e32 v0, 0xffff8000, v0
	v_bitop3_b32 v7, v5, v6, v3 bitop3:0x36
	v_or_b32_e32 v3, v5, v3
	v_lshlrev_b32_e32 v2, 10, v2
	s_waitcnt vmcnt(6)
	v_lshl_add_u32 v0, v13, 11, v0
	v_and_b32_e32 v1, 1, v12
	v_or3_b32 v4, v4, s3, v7
	v_bitop3_b32 v173, v3, v2, v6 bitop3:0xde
	v_lshl_or_b32 v0, v1, 6, v0
	s_add_i32 s64, 0, 0x10000
	s_add_i32 s65, 0, 0x14000
	v_or_b32_e32 v172, s57, v139
	v_mov_b32_e32 v141, v137
	v_lshl_add_u32 v142, v14, 1, v0
	v_mov_b32_e32 v143, v137
	v_mov_b64_e32 v[144:145], 0x400
	v_mov_b64_e32 v[146:147], 0x3ff
	v_add_u32_e32 v175, s64, v173
	v_add_u32_e32 v176, s65, v173
	v_add_u32_e32 v177, 0, v4
	s_mov_b32 s66, 0
	s_barrier
	s_branch .LBB5_241

.LBB5_453:
	s_add_u32 s10, s72, 0x10000000
	s_addc_u32 s11, s73, 0
	s_add_u32 s12, s72, 0xc000000
	v_readlane_b32 s3, v250, 29
	s_addc_u32 s13, s73, 0
	s_lshl_b32 s3, s3, 5
	s_and_b32 s21, s3, 0x60
	s_lshl_b32 s20, s1, 13
	s_lshr_b32 s22, s21, 3
	v_readlane_b32 s3, v250, 0
	s_cmpk_lt_u32 s3, 0x100
	s_mov_b64 s[16:17], 0x80
	s_cselect_b64 s[14:15], -1, 0
	v_lshl_add_u64 v[6:7], v[6:7], 0, s[16:17]
	s_add_i32 m0, s39, 0x18000
	s_ashr_i32 s52, s90, 31
	global_load_lds_dwordx4 v[6:7], off
	v_lshl_add_u64 v[4:5], v[4:5], 0, s[16:17]
	s_add_i32 m0, s39, 0x1a000
	s_add_i32 s53, s39, 0x8000
	s_add_i32 s54, s39, 0xa000
	global_load_lds_dwordx4 v[4:5], off
	v_lshl_add_u64 v[2:3], v[2:3], 0, s[16:17]
	s_mov_b32 m0, s53
	s_add_u32 s18, s42, 0x40080
	global_load_lds_dwordx4 v[2:3], off
	v_lshl_add_u64 v[0:1], v[0:1], 0, s[16:17]
	s_mov_b32 m0, s54
	s_addc_u32 s19, s43, 0
	global_load_lds_dwordx4 v[0:1], off
	v_lshl_add_u64 v[0:1], s[18:19], 0, v[202:203]
	s_add_i32 m0, s39, 0x1c000
	v_lshrrev_b32_e32 v2, 6, v9
	global_load_lds_dwordx4 v[0:1], off
	v_lshl_add_u64 v[0:1], s[18:19], 0, v[206:207]
	s_add_i32 m0, s39, 0x1e000
	v_lshlrev_b32_e32 v5, 2, v9
	global_load_lds_dwordx4 v[0:1], off
	s_waitcnt vmcnt(8)
	s_barrier
	v_and_b32_e32 v0, 15, v9
	v_lshl_or_b32 v226, s1, 6, v0
	v_and_b32_e32 v3, 48, v9
	v_lshlrev_b32_e32 v4, 10, v2
	v_lshlrev_b32_e32 v0, 6, v0
	v_and_b32_e32 v5, 32, v5
	v_or_b32_e32 v2, s22, v2
	v_bitop3_b32 v6, v0, v5, v3 bitop3:0x36
	v_or_b32_e32 v0, v0, v3
	v_lshlrev_b32_e32 v2, 10, v2
	v_lshrrev_b32_e32 v1, 1, v9
	v_bitop3_b32 v227, v0, v2, v5 bitop3:0xde
	v_lshlrev_b32_e32 v0, 14, v8
	v_and_b32_e32 v1, 56, v1
	v_and_b32_e32 v0, 0xffff8000, v0
	v_add_u32_e32 v228, s21, v1
	v_lshl_add_u32 v0, v10, 11, v0
	v_and_b32_e32 v1, 1, v8
	v_lshl_or_b32 v0, v1, 6, v0
	v_lshl_add_u32 v208, v11, 1, v0
	v_lshlrev_b32_e32 v0, 14, v12
	v_and_b32_e32 v0, 0xffff8000, v0
	s_waitcnt vmcnt(6)
	v_lshl_add_u32 v0, v13, 11, v0
	v_and_b32_e32 v1, 1, v12
	v_or3_b32 v4, v4, s20, v6
	v_lshl_or_b32 v0, v1, 6, v0
	s_add_i32 s55, 0, 0x10000
	s_add_i32 s56, 0, 0x14000
	s_sext_i32_i8 s3, s0
	v_mov_b32_e32 v209, v203
	v_lshl_add_u32 v210, v14, 1, v0
	v_mov_b32_e32 v211, v203
	v_mov_b64_e32 v[212:213], 0x200
	v_mov_b64_e32 v[214:215], 0x1ff
	v_add_u32_e32 v229, s55, v227
	v_add_u32_e32 v230, s56, v227
	v_add_u32_e32 v231, 0, v4
	s_barrier
	s_branch .LBB5_456

.LBB5_526:
	s_add_u32 s12, s72, 0x2800000
	v_readlane_b32 s4, v250, 0
	s_addc_u32 s13, s73, 0
	s_bfe_u32 s46, s4, 0x20006
	s_lshl_b32 s1, s0, 13
	s_lshl_b32 s18, s46, 12
	s_cmpk_lt_u32 s4, 0x100
	s_mov_b64 s[16:17], 0x80
	s_cselect_b64 s[14:15], -1, 0
	v_lshl_add_u64 v[6:7], v[6:7], 0, s[16:17]
	s_add_i32 m0, s31, 0x18000
	s_ashr_i32 s47, s90, 31
	s_ashr_i32 s48, s2, 31
	global_load_lds_dwordx4 v[6:7], off
	v_lshl_add_u64 v[4:5], v[4:5], 0, s[16:17]
	s_add_i32 m0, s31, 0x1a000
	s_add_i32 s49, s31, 0x8000
	s_add_i32 s50, s31, 0xa000
	global_load_lds_dwordx4 v[4:5], off
	v_lshl_add_u64 v[2:3], v[2:3], 0, s[16:17]
	s_mov_b32 m0, s49
	s_add_u32 s4, s42, 0x40080
	global_load_lds_dwordx4 v[2:3], off
	v_lshl_add_u64 v[0:1], v[0:1], 0, s[16:17]
	s_mov_b32 m0, s50
	s_addc_u32 s5, s43, 0
	global_load_lds_dwordx4 v[0:1], off
	v_lshl_add_u64 v[0:1], s[4:5], 0, v[178:179]
	s_add_i32 m0, s31, 0x1c000
	v_lshlrev_b32_e32 v4, 2, v8
	global_load_lds_dwordx4 v[0:1], off
	v_lshl_add_u64 v[0:1], s[4:5], 0, v[182:183]
	s_add_i32 m0, s31, 0x1e000
	v_and_b32_e32 v2, 48, v8
	global_load_lds_dwordx4 v[0:1], off
	s_waitcnt vmcnt(8)
	s_barrier
	v_and_b32_e32 v0, 15, v8
	v_lshrrev_b32_e32 v1, 1, v8
	v_lshl_or_b32 v204, s0, 6, v0
	v_and_b32_e32 v1, 56, v1
	v_lshlrev_b32_e32 v0, 6, v0
	v_and_b32_e32 v4, 32, v4
	v_and_b32_e32 v3, 0x400, v12
	v_bitop3_b32 v0, v0, v4, v2 bitop3:0x36
	v_lshl_add_u32 v206, s46, 5, v1
	v_and_b32_e32 v1, 64, v8
	v_or3_b32 v2, v3, s1, v0
	v_or3_b32 v205, v3, s18, v0
	v_xor_b32_e32 v0, 16, v8
	v_add_u32_e32 v1, 64, v1
	v_cmp_lt_i32_e32 vcc, v0, v1
	s_waitcnt vmcnt(6)
	s_add_i32 s51, 0, 0x10000
	s_add_i32 s52, 0, 0x14000
	v_cndmask_b32_e32 v0, v8, v0, vcc
	v_lshlrev_b32_e32 v207, 2, v0
	v_xor_b32_e32 v0, 32, v8
	v_cmp_lt_i32_e32 vcc, v0, v1
	v_and_b32_e32 v1, 1, v9
	v_cmp_gt_u32_e64 s[0:1], 16, v8
	v_cndmask_b32_e32 v0, v8, v0, vcc
	v_lshlrev_b32_e32 v208, 2, v0
	v_lshlrev_b32_e32 v0, 14, v9
	v_and_b32_e32 v0, 0xffff8000, v0
	v_lshl_add_u32 v0, v10, 11, v0
	v_lshl_or_b32 v0, v1, 6, v0
	v_lshl_add_u32 v184, v11, 1, v0
	v_lshlrev_b32_e32 v0, 14, v13
	v_and_b32_e32 v0, 0xffff8000, v0
	v_lshl_add_u32 v0, v14, 11, v0
	v_and_b32_e32 v1, 1, v13
	v_lshl_or_b32 v0, v1, 6, v0
	v_mov_b32_e32 v185, v179
	v_lshl_add_u32 v186, v15, 1, v0
	v_mov_b32_e32 v187, v179
	v_mov_b64_e32 v[188:189], 0x200
	v_mov_b64_e32 v[190:191], 0x1ff
	v_add_u32_e32 v209, s51, v205
	v_add_u32_e32 v210, s52, v205
	v_add_u32_e32 v211, 0, v2
	s_mov_b32 s53, 0
	s_barrier
	s_branch .LBB5_529

.LBB5_615:
	s_add_u32 s18, s72, 0xc000000
	s_addc_u32 s19, s73, 0
	s_add_u32 s20, s72, 0x10000000
	s_addc_u32 s21, s73, 0
	s_add_u32 s22, s72, 0x14000000
	s_addc_u32 s23, s73, 0
	s_add_u32 s26, s72, 0x18000000
	s_addc_u32 s27, s73, 0
	s_add_u32 s36, s72, 0x2800000
	s_addc_u32 s37, s73, 0
	s_add_u32 s38, s72, 0x2600000
	s_addc_u32 s39, s73, 0
	s_add_u32 s40, s72, 0x2640000
	v_readlane_b32 s10, v250, 0
	s_addc_u32 s41, s73, 0
	s_bfe_u32 s1, s10, 0x20006
	s_lshl_b32 s3, s0, 13
	s_lshl_b32 s5, s1, 5
	s_lshl_b32 s1, s1, 12
	s_cmpk_lt_u32 s10, 0x100
	s_cselect_b64 s[42:43], -1, 0
	s_bitcmp0_b32 s10, 6
	s_mov_b64 s[46:47], 0x80
	s_cselect_b64 s[44:45], -1, 0
	v_lshl_add_u64 v[6:7], v[6:7], 0, s[46:47]
	s_add_i32 m0, s61, 0x18000
	s_ashr_i32 s66, s90, 31
	s_ashr_i32 s67, s2, 31
	global_load_lds_dwordx4 v[6:7], off
	v_lshl_add_u64 v[4:5], v[4:5], 0, s[46:47]
	s_add_i32 m0, s61, 0x1a000
	s_add_i32 s78, s61, 0x8000
	s_add_i32 s79, s61, 0xa000
	global_load_lds_dwordx4 v[4:5], off
	v_lshl_add_u64 v[2:3], v[2:3], 0, s[46:47]
	s_mov_b32 m0, s78
	s_add_u32 s10, s8, 0x40080
	global_load_lds_dwordx4 v[2:3], off
	v_lshl_add_u64 v[0:1], v[0:1], 0, s[46:47]
	s_mov_b32 m0, s79
	s_addc_u32 s11, s9, 0
	global_load_lds_dwordx4 v[0:1], off
	v_lshl_add_u64 v[0:1], s[10:11], 0, v[162:163]
	s_add_i32 m0, s61, 0x1c000
	v_lshlrev_b32_e32 v4, 2, v8
	global_load_lds_dwordx4 v[0:1], off
	v_lshl_add_u64 v[0:1], s[10:11], 0, v[166:167]
	s_add_i32 m0, s61, 0x1e000
	v_and_b32_e32 v2, 48, v8
	global_load_lds_dwordx4 v[0:1], off
	s_waitcnt vmcnt(8)
	s_barrier
	v_and_b32_e32 v0, 15, v8
	v_lshl_or_b32 v182, s0, 6, v0
	v_lshlrev_b32_e32 v0, 6, v0
	v_and_b32_e32 v4, 32, v4
	v_lshrrev_b32_e32 v1, 4, v8
	v_and_b32_e32 v3, 0x400, v12
	v_bitop3_b32 v0, v0, v4, v2 bitop3:0x36
	v_or3_b32 v183, v3, s1, v0
	v_lshl_add_u32 v184, v1, 3, s5
	v_cmp_gt_i32_e64 s[0:1], 2, v1
	v_and_b32_e32 v1, 64, v8
	v_or3_b32 v2, v3, s3, v0
	v_cmp_gt_u32_e32 vcc, 16, v8
	v_xor_b32_e32 v0, 16, v8
	v_add_u32_e32 v1, 64, v1
	v_cndmask_b32_e64 v170, 1.0, -1.0, vcc
	v_cmp_lt_i32_e32 vcc, v0, v1
	v_and_b32_e32 v1, 1, v9
	s_waitcnt vmcnt(6)
	s_add_i32 s80, 0, 0x10000
	v_cndmask_b32_e32 v0, v8, v0, vcc
	v_lshlrev_b32_e32 v185, 2, v0
	v_lshlrev_b32_e32 v0, 14, v9
	v_and_b32_e32 v0, 0xffff8000, v0
	v_lshl_add_u32 v0, v10, 11, v0
	v_lshl_or_b32 v0, v1, 6, v0
	v_lshl_add_u32 v172, v11, 1, v0
	v_lshlrev_b32_e32 v0, 14, v13
	v_and_b32_e32 v0, 0xffff8000, v0
	v_lshl_add_u32 v0, v14, 11, v0
	v_and_b32_e32 v1, 1, v13
	v_lshl_or_b32 v0, v1, 6, v0
	s_add_i32 s81, 0, 0x14000
	v_mov_b32_e32 v171, v170
	v_mov_b32_e32 v173, v169
	v_lshl_add_u32 v174, v15, 1, v0
	v_mov_b32_e32 v175, v169
	v_mov_b64_e32 v[176:177], 0x800
	v_mov_b64_e32 v[178:179], 0x7ff
	v_add_u32_e32 v186, s80, v183
	v_add_u32_e32 v187, s81, v183
	v_add_u32_e32 v188, 0, v2
	v_mov_b32_e32 v189, 0x358637bd
	s_mov_b32 s82, 0xf800000
	v_mov_b32_e32 v190, 0x260
	s_barrier
	s_branch .LBB5_618

.LBB5_959:
	s_add_u32 s12, s72, 0x14000000
	s_addc_u32 s13, s73, 0
	s_add_u32 s14, s72, 0x2a00000
	v_readlane_b32 s4, v250, 0
	s_addc_u32 s15, s73, 0
	s_bfe_u32 s46, s4, 0x20006
	s_lshl_b32 s1, s0, 13
	s_lshl_b32 s20, s46, 12
	s_cmpk_lt_u32 s4, 0x100
	s_mov_b64 s[18:19], 0x80
	s_cselect_b64 s[16:17], -1, 0
	v_lshl_add_u64 v[6:7], v[6:7], 0, s[18:19]
	s_add_i32 m0, s34, 0x18000
	s_ashr_i32 s47, s90, 31
	s_ashr_i32 s48, s2, 31
	global_load_lds_dwordx4 v[6:7], off
	v_lshl_add_u64 v[4:5], v[4:5], 0, s[18:19]
	s_add_i32 m0, s34, 0x1a000
	s_add_i32 s49, s34, 0x8000
	s_add_i32 s50, s34, 0xa000
	global_load_lds_dwordx4 v[4:5], off
	v_lshl_add_u64 v[2:3], v[2:3], 0, s[18:19]
	s_mov_b32 m0, s49
	s_add_u32 s4, s40, 0x40080
	global_load_lds_dwordx4 v[2:3], off
	v_lshl_add_u64 v[0:1], v[0:1], 0, s[18:19]
	s_mov_b32 m0, s50
	s_addc_u32 s5, s41, 0
	global_load_lds_dwordx4 v[0:1], off
	v_lshl_add_u64 v[0:1], s[4:5], 0, v[154:155]
	s_add_i32 m0, s34, 0x1c000
	v_lshlrev_b32_e32 v4, 2, v8
	global_load_lds_dwordx4 v[0:1], off
	v_lshl_add_u64 v[0:1], s[4:5], 0, v[158:159]
	s_add_i32 m0, s34, 0x1e000
	v_and_b32_e32 v2, 48, v8
	global_load_lds_dwordx4 v[0:1], off
	s_waitcnt vmcnt(8)
	s_barrier
	v_and_b32_e32 v0, 15, v8
	v_lshrrev_b32_e32 v1, 1, v8
	v_lshl_or_b32 v186, s0, 6, v0
	v_and_b32_e32 v1, 56, v1
	v_lshlrev_b32_e32 v0, 6, v0
	v_and_b32_e32 v4, 32, v4
	v_and_b32_e32 v3, 0x400, v12
	v_bitop3_b32 v0, v0, v4, v2 bitop3:0x36
	v_lshl_add_u32 v188, s46, 5, v1
	v_and_b32_e32 v1, 64, v8
	v_or3_b32 v2, v3, s1, v0
	v_or3_b32 v187, v3, s20, v0
	v_xor_b32_e32 v0, 16, v8
	v_add_u32_e32 v1, 64, v1
	v_cmp_lt_i32_e32 vcc, v0, v1
	s_waitcnt vmcnt(6)
	s_add_i32 s51, 0, 0x10000
	s_add_i32 s52, 0, 0x14000
	v_cndmask_b32_e32 v0, v8, v0, vcc
	v_lshlrev_b32_e32 v189, 2, v0
	v_xor_b32_e32 v0, 32, v8
	v_cmp_lt_i32_e32 vcc, v0, v1
	v_and_b32_e32 v1, 1, v9
	v_cmp_gt_u32_e64 s[0:1], 16, v8
	v_cndmask_b32_e32 v0, v8, v0, vcc
	v_lshlrev_b32_e32 v190, 2, v0
	v_lshlrev_b32_e32 v0, 14, v9
	v_and_b32_e32 v0, 0xffff8000, v0
	v_lshl_add_u32 v0, v10, 11, v0
	v_lshl_or_b32 v0, v1, 6, v0
	v_lshl_add_u32 v160, v11, 1, v0
	v_lshlrev_b32_e32 v0, 14, v13
	v_and_b32_e32 v0, 0xffff8000, v0
	v_lshl_add_u32 v0, v14, 11, v0
	v_and_b32_e32 v1, 1, v13
	v_lshl_or_b32 v0, v1, 6, v0
	v_mov_b32_e32 v161, v155
	v_lshl_add_u32 v162, v15, 1, v0
	v_mov_b32_e32 v163, v155
	v_mov_b64_e32 v[164:165], 0x200
	v_mov_b64_e32 v[166:167], 0x1ff
	v_add_u32_e32 v191, s51, v187
	v_add_u32_e32 v192, s52, v187
	v_add_u32_e32 v193, 0, v2
	s_mov_b32 s53, 0
	s_barrier
	s_branch .LBB5_962
